# R4 mid-loop wait: L1 invalidate issued before the poll as in the other barriers
# baseline (speedup 1.0000x reference)
.LBB0_995:
	s_cmp_lg_u32 s20, 2
	s_cbranch_scc1 .Lr4_nowait
	s_cmp_eq_u32 s21, 0
	s_cbranch_scc1 .Lr4_nowait
	s_mov_b64 s[22:23], exec
	v_readlane_b32 s24, v254, 2
	v_readlane_b32 s25, v254, 3
	s_nop 1
	s_and_b64 s[24:25], s[22:23], s[24:25]
	s_mov_b64 exec, s[24:25]
	s_cbranch_execz .Lr4_wait_join
	v_mov_b32_e32 v2, 0x23fc4
	ds_read_b32 v3, v2
	s_add_u32 s26, s62, 0x408000
	s_addc_u32 s27, s63, 0
	v_mov_b32_e32 v2, 0x400
	s_mov_b32 s28, 0
	buffer_inv sc1

.Lr4_spin_done:
.Lr4_wait_join:
	s_mov_b64 exec, s[22:23]
	s_barrier
